# APP: prompt attention unit prologue - tile-skip inputs (PF, CLT, N2 per lane group) and 4th K-row fragment issued with the unit's first loads instead of 6 serialized round trips
# baseline (speedup 1.0000x reference)
; __device__ __forceinline__ void attn_unit(const Args& a, LAS unsigned char* lds, const int mode, const int h, const int qb, const int tid_in, const int lane_in, const int wave) {
;     ...
;     const int qrow = mode == 0 ? qb * 256 + wave * 32 + r32 : MP + qb * 64 + (wave & 1) * 32 + r32;
;     const int qpos = mode == 0 ? qrow : PAST + (wave & 1) * 32 + r32;
;     const int qfirst = qpos - r32;
;     float cq2; bf16x8 qr[4];
;     { const float pfx = mode == 0 ? ((const float*)(ws + WS_PFXP))[h * 256 + (qrow >> 6)] : ((const float*)(ws + WS_PFXS))[qb * 16 + h];
;       cq2 = (pfx + CLT[qrow]) * L2E;
; #pragma unroll
;       for (int d0 = 0; d0 < 4; ++d0) qr[d0] = *(const bf16x8*)(Qb + (size_t)qrow * D + h * HD + d0 * 16 + hi * 8); }
;     ...
;         for (int d0 = 0; d0 < 4; ++d0) { const u32x4 kw = *(const u32x4*)(Kb + (size_t)qrow * D + h * HD + d0 * 16 + hi * 8); const u32x4 qw = __builtin_bit_cast(u32x4, qr[d0]);
;             const unsigned kk[4] = {kw.x, kw.y, kw.z, kw.w}; const unsigned qq[4] = {qw.x, qw.y, qw.z, qw.w};
; #pragma unroll
;             for (int e = 0; e < 4; ++e) dsc += __uint_as_float(kk[e] << 16) * __uint_as_float(qq[e] << 16) + __uint_as_float(kk[e] & 0xffff0000u) * __uint_as_float(qq[e] & 0xffff0000u); }
;         dsc += __shfl_xor(dsc, 32);
; #pragma unroll
;         for (int o = 1; o < 32; o <<= 1) dsc = fminf(dsc, __shfl_xor(dsc, o));
;         float qsq = 0.f;
; #pragma unroll
;         for (int d0 = 0; d0 < 4; ++d0) { const u32x4 qw = __builtin_bit_cast(u32x4, qr[d0]); const unsigned qq[4] = {qw.x, qw.y, qw.z, qw.w};
; #pragma unroll
;             for (int e = 0; e < 4; ++e) { const float lo = __uint_as_float(qq[e] << 16), hi_ = __uint_as_float(qq[e] & 0xffff0000u); qsq += lo * lo + hi_ * hi_; } }
;         qsq += __shfl_xor(qsq, 32);
; #pragma unroll
;         for (int o = 1; o < 32; o <<= 1) qsq = fmaxf(qsq, __shfl_xor(qsq, o));
;         LAS float* red = (LAS float*)(lds + AT_END);
;         if (lane == 0) { red[wave] = dsc; red[8 + wave] = qsq; }
;         __syncthreads();
;         float dmin = red[0], qn = red[8];
; #pragma unroll
;         for (int w = 1; w < 8; ++w) { dmin = fminf(dmin, red[w]); qn = fmaxf(qn, red[8 + w]); }
;         const float* N2 = (const float*)(ws + WS_N2); const float* PF = (const float*)(ws + WS_PFXP) + h * 256;
;         const float cq0 = (PF[qb * 4] + CLT[qb * 256]) * L2E, base = cq0 - dmin + 0.05f + 30.f;
.LBB0_501:
	s_andn2_b64 vcc, exec, s[0:1]
	s_cbranch_vccnz .LBB0_542
	s_add_i32 s0, s68, 0xffffff00
	s_and_b32 s17, s68, 15
	s_lshr_b32 s0, s0, 4
	s_sub_i32 s1, 63, s0
	s_mul_i32 s2, s17, 0x11000
	v_readlane_b32 s3, v254, 28
	s_add_u32 s8, s3, s2
	v_readlane_b32 s2, v254, 30
	v_mov_b32_e32 v1, v134
	s_addc_u32 s9, s2, 0
	s_lshl_b32 s2, s1, 8
	v_readlane_b32 s3, v254, 25
	s_add_i32 s3, s2, s3
	v_and_b32_e32 v6, 31, v1
	v_or_b32_e32 v92, s3, v6
	s_lshl_b32 s15, s17, 8
	s_lshr_b32 s3, s3, 6
	v_mov_b32_e32 v93, v0
	v_readlane_b32 s4, v254, 26
	s_add_i32 s3, s3, s15
	v_lshlrev_b64 v[2:3], 11, v[92:93]
	v_readlane_b32 s5, v254, 27
	v_bfe_u32 v7, v1, 5, 1
	s_lshl_b32 s3, s3, 2
	v_lshl_add_u64 v[8:9], s[4:5], 0, v[2:3]
	s_lshl_b32 s72, s17, 7
	v_mov_b32_e32 v14, s3
	v_lshl_add_u64 v[8:9], v[8:9], 0, s[72:73]
	v_lshlrev_b32_e32 v10, 4, v7
	v_mov_b32_e32 v11, v0
	v_lshl_add_u64 v[4:5], v[92:93], 2, s[8:9]
	v_lshl_add_u64 v[12:13], v[8:9], 0, v[10:11]
	global_load_dword v9, v14, s[60:61]
	global_load_dword v10, v[4:5], off
	global_load_dwordx4 v[66:69], v[12:13], off
	global_load_dwordx4 v[70:73], v[12:13], off offset:32
	global_load_dwordx4 v[74:77], v[12:13], off offset:64
	global_load_dwordx4 v[78:81], v[12:13], off offset:96
	s_lshl_b32 s16, s1, 2
	s_lshl_b32 s14, s17, 6
	v_and_b32_e32 v8, 63, v1
	v_lshlrev_b32_e32 v90, 3, v7
	s_cmp_eq_u32 s0, 63
	s_mov_b32 s12, 0
	s_cbranch_scc1 .LBB0_514
	v_lshl_add_u64 v[2:3], s[38:39], 0, v[2:3]
	s_lshl_b32 s72, s14, 1
	v_lshl_add_u64 v[2:3], v[2:3], 0, s[72:73]
	v_lshlrev_b32_e32 v4, 1, v90
	v_mov_b32_e32 v5, v0
	v_lshl_add_u64 v[2:3], v[2:3], 0, v[4:5]
	global_load_dwordx4 v[16:19], v[2:3], off
	global_load_dwordx4 v[24:27], v[2:3], off offset:32
	global_load_dwordx4 v[32:35], v[2:3], off offset:64
	global_load_dwordx4 v[236:239], v[2:3], off offset:96
	s_lshl_b32 s100, s15, 2
	s_add_u32 s100, s60, s100
	s_addc_u32 s101, s61, 0
	s_lshl_b32 s99, s16, 2
	v_mov_b32_e32 v200, s99
	s_lshl_b32 s99, s2, 2
	v_mov_b32_e32 v201, s99
	v_lshlrev_b32_e32 v202, 2, v8
	global_load_dword v240, v200, s[100:101]
	global_load_dword v241, v201, s[8:9]
	global_load_dword v242, v202, s[100:101] offset:4
	global_load_dword v243, v202, s[100:101] offset:260
	global_load_dword v244, v202, s[100:101] offset:516
	global_load_dword v245, v202, s[100:101] offset:772
	s_lshl_b32 s99, s17, 2
	v_lshl_or_b32 v204, v8, 7, s99
	v_mov_b32_e32 v205, v0
	v_lshl_add_u64 v[204:205], s[88:89], 0, v[204:205]
	s_mov_b64 s[98:99], 0x191040
	v_lshl_add_u64 v[204:205], v[204:205], 0, s[98:99]
	s_mov_b64 s[98:99], 0x2000
	global_load_dword v246, v[204:205], off
	v_lshl_add_u64 v[204:205], v[204:205], 0, s[98:99]
	global_load_dword v247, v[204:205], off
	v_lshl_add_u64 v[204:205], v[204:205], 0, s[98:99]
	global_load_dword v248, v[204:205], off
	v_lshl_add_u64 v[204:205], v[204:205], 0, s[98:99]
	global_load_dword v249, v[204:205], off
	s_waitcnt vmcnt(17)
	v_and_b32_e32 v12, 0xffff0000, v66
	v_lshlrev_b32_e32 v11, 16, v66
	v_and_b32_e32 v15, 0xffff0000, v67
	v_lshlrev_b32_e32 v13, 16, v67
	s_waitcnt vmcnt(16)
	v_and_b32_e32 v21, 0xffff0000, v70
	v_and_b32_e32 v23, 0xffff0000, v71
	s_waitcnt vmcnt(15)
	v_and_b32_e32 v29, 0xffff0000, v74
	v_and_b32_e32 v31, 0xffff0000, v75
	s_waitcnt vmcnt(14)
	v_and_b32_e32 v38, 0xffff0000, v78
	v_lshlrev_b32_e32 v37, 16, v78
	v_and_b32_e32 v39, 0xffff0000, v79
	v_and_b32_e32 v40, 0xffff0000, v80
	v_and_b32_e32 v41, 0xffff0000, v81
	s_waitcnt vmcnt(13)
	v_and_b32_e32 v5, 0xffff0000, v16
	v_lshlrev_b32_e32 v4, 16, v16
	v_mul_f32_e32 v5, v12, v5
	v_fmac_f32_e32 v5, v11, v4
	v_and_b32_e32 v14, 0xffff0000, v17
	v_add_f32_e32 v4, 0, v5
	v_lshlrev_b32_e32 v5, 16, v17
	v_mul_f32_e32 v14, v15, v14
	v_fmac_f32_e32 v14, v13, v5
	v_and_b32_e32 v16, 0xffff0000, v18
	v_and_b32_e32 v17, 0xffff0000, v68
	v_add_f32_e32 v4, v14, v4
	v_lshlrev_b32_e32 v5, 16, v18
	v_lshlrev_b32_e32 v14, 16, v68
	v_mul_f32_e32 v16, v17, v16
	v_fmac_f32_e32 v16, v14, v5
	v_lshlrev_b32_e32 v5, 16, v19
	v_and_b32_e32 v19, 0xffff0000, v19
	v_and_b32_e32 v18, 0xffff0000, v69
	v_add_f32_e32 v4, v16, v4
	v_lshlrev_b32_e32 v16, 16, v69
	v_mul_f32_e32 v19, v18, v19
	v_fmac_f32_e32 v19, v16, v5
	s_waitcnt vmcnt(12)
	v_and_b32_e32 v20, 0xffff0000, v24
	v_add_f32_e32 v4, v19, v4
	v_lshlrev_b32_e32 v5, 16, v24
	v_lshlrev_b32_e32 v19, 16, v70
	v_mul_f32_e32 v20, v21, v20
	v_fmac_f32_e32 v20, v19, v5
	v_and_b32_e32 v22, 0xffff0000, v25
	v_add_f32_e32 v4, v20, v4
	v_lshlrev_b32_e32 v5, 16, v25
	v_lshlrev_b32_e32 v20, 16, v71
	v_mul_f32_e32 v22, v23, v22
	v_fmac_f32_e32 v22, v20, v5
	v_and_b32_e32 v24, 0xffff0000, v26
	v_and_b32_e32 v25, 0xffff0000, v72
	v_add_f32_e32 v4, v22, v4
	v_lshlrev_b32_e32 v5, 16, v26
	v_lshlrev_b32_e32 v22, 16, v72
	v_mul_f32_e32 v24, v25, v24
	v_fmac_f32_e32 v24, v22, v5
	v_lshlrev_b32_e32 v5, 16, v27
	v_and_b32_e32 v27, 0xffff0000, v27
	v_and_b32_e32 v26, 0xffff0000, v73
	v_add_f32_e32 v4, v24, v4
	v_lshlrev_b32_e32 v24, 16, v73
	v_mul_f32_e32 v27, v26, v27
	v_fmac_f32_e32 v27, v24, v5
	s_waitcnt vmcnt(11)
	v_and_b32_e32 v28, 0xffff0000, v32
	v_add_f32_e32 v4, v27, v4
	v_lshlrev_b32_e32 v5, 16, v32
	v_lshlrev_b32_e32 v27, 16, v74
	v_mul_f32_e32 v28, v29, v28
	v_fmac_f32_e32 v28, v27, v5
	v_and_b32_e32 v30, 0xffff0000, v33
	v_add_f32_e32 v4, v28, v4
	v_lshlrev_b32_e32 v5, 16, v33
	v_lshlrev_b32_e32 v28, 16, v75
	v_mul_f32_e32 v30, v31, v30
	v_fmac_f32_e32 v30, v28, v5
	v_and_b32_e32 v32, 0xffff0000, v34
	v_and_b32_e32 v33, 0xffff0000, v76
	v_add_f32_e32 v4, v30, v4
	v_lshlrev_b32_e32 v5, 16, v34
	v_lshlrev_b32_e32 v30, 16, v76
	v_mul_f32_e32 v32, v33, v32
	v_fmac_f32_e32 v32, v30, v5
	v_lshlrev_b32_e32 v5, 16, v35
	v_and_b32_e32 v35, 0xffff0000, v35
	v_and_b32_e32 v34, 0xffff0000, v77
	v_add_f32_e32 v4, v32, v4
	v_lshlrev_b32_e32 v32, 16, v77
	v_mul_f32_e32 v35, v34, v35
	v_fmac_f32_e32 v35, v32, v5
	v_add_f32_e32 v35, v35, v4
	s_waitcnt vmcnt(10)
; #define LAS __attribute__((address_space(3)))
; __device__ __forceinline__ void attn_unit(const Args& a, LAS unsigned char* lds, const int mode, const int h, const int qb, const int tid_in, const int lane_in, const int wave) {
;     ...
;         for (int d0 = 0; d0 < 4; ++d0) { const u32x4 kw = *(const u32x4*)(Kb + (size_t)qrow * D + h * HD + d0 * 16 + hi * 8); const u32x4 qw = __builtin_bit_cast(u32x4, qr[d0]);
;             const unsigned kk[4] = {kw.x, kw.y, kw.z, kw.w}; const unsigned qq[4] = {qw.x, qw.y, qw.z, qw.w};
; #pragma unroll
;             for (int e = 0; e < 4; ++e) dsc += __uint_as_float(kk[e] << 16) * __uint_as_float(qq[e] << 16) + __uint_as_float(kk[e] & 0xffff0000u) * __uint_as_float(qq[e] & 0xffff0000u); }
;         dsc += __shfl_xor(dsc, 32);
; #pragma unroll
;         for (int o = 1; o < 32; o <<= 1) dsc = fminf(dsc, __shfl_xor(dsc, o));
;         float qsq = 0.f;
; #pragma unroll
;         for (int d0 = 0; d0 < 4; ++d0) { const u32x4 qw = __builtin_bit_cast(u32x4, qr[d0]); const unsigned qq[4] = {qw.x, qw.y, qw.z, qw.w};
; #pragma unroll
;             for (int e = 0; e < 4; ++e) { const float lo = __uint_as_float(qq[e] << 16), hi_ = __uint_as_float(qq[e] & 0xffff0000u); qsq += lo * lo + hi_ * hi_; } }
;         qsq += __shfl_xor(qsq, 32);
; #pragma unroll
;         for (int o = 1; o < 32; o <<= 1) qsq = fmaxf(qsq, __shfl_xor(qsq, o));
;         LAS float* red = (LAS float*)(lds + AT_END);
;         if (lane == 0) { red[wave] = dsc; red[8 + wave] = qsq; }
	v_mov_b32_e32 v2, v236
	v_mov_b32_e32 v3, v237
	v_mov_b32_e32 v4, v238
	v_mov_b32_e32 v5, v239
	v_mul_f32_e32 v12, v12, v12
	v_fmac_f32_e32 v12, v11, v11
	v_mul_f32_e32 v11, v15, v15
	v_fmac_f32_e32 v11, v13, v13
	v_add_f32_e32 v11, v12, v11
	v_mul_f32_e32 v12, v17, v17
	v_fmac_f32_e32 v12, v14, v14
	v_add_f32_e32 v11, v12, v11
	v_mul_f32_e32 v12, v18, v18
	v_fmac_f32_e32 v12, v16, v16
	v_add_f32_e32 v11, v12, v11
	v_mul_f32_e32 v12, v21, v21
	v_fmac_f32_e32 v12, v19, v19
	v_add_f32_e32 v11, v12, v11
	v_mul_f32_e32 v12, v23, v23
	v_fmac_f32_e32 v12, v20, v20
	v_add_f32_e32 v11, v12, v11
	v_mul_f32_e32 v12, v25, v25
	v_fmac_f32_e32 v12, v22, v22
	v_add_f32_e32 v11, v12, v11
	v_mul_f32_e32 v12, v26, v26
	v_fmac_f32_e32 v12, v24, v24
	v_add_f32_e32 v11, v12, v11
	v_mul_f32_e32 v12, v29, v29
	v_fmac_f32_e32 v12, v27, v27
	v_add_f32_e32 v11, v12, v11
	v_mul_f32_e32 v12, v31, v31
	v_fmac_f32_e32 v12, v28, v28
	v_add_f32_e32 v11, v12, v11
	v_mul_f32_e32 v12, v33, v33
	v_fmac_f32_e32 v12, v30, v30
	v_add_f32_e32 v11, v12, v11
	v_mul_f32_e32 v12, v34, v34
	v_fmac_f32_e32 v12, v32, v32
	v_add_f32_e32 v11, v12, v11
	v_mul_f32_e32 v12, v38, v38
	v_fmac_f32_e32 v12, v37, v37
	v_add_f32_e32 v11, v12, v11
	v_mul_f32_e32 v12, v39, v39
	s_waitcnt vmcnt(0)
	v_lshlrev_b32_e32 v36, 16, v2
	v_and_b32_e32 v2, 0xffff0000, v2
	v_mul_f32_e32 v2, v38, v2
	v_fmac_f32_e32 v2, v37, v36
	v_add_f32_e32 v2, v2, v35
	v_lshlrev_b32_e32 v35, 16, v3
	v_and_b32_e32 v3, 0xffff0000, v3
	v_lshlrev_b32_e32 v36, 16, v79
	v_mul_f32_e32 v3, v39, v3
	v_fmac_f32_e32 v3, v36, v35
	v_add_f32_e32 v2, v3, v2
	v_lshlrev_b32_e32 v3, 16, v4
	v_and_b32_e32 v4, 0xffff0000, v4
	v_lshlrev_b32_e32 v35, 16, v80
	v_mul_f32_e32 v4, v40, v4
	v_fmac_f32_e32 v4, v35, v3
	v_lshlrev_b32_e32 v3, 16, v5
	v_and_b32_e32 v5, 0xffff0000, v5
	v_add_f32_e32 v2, v4, v2
	v_lshlrev_b32_e32 v4, 16, v81
	v_mul_f32_e32 v5, v41, v5
	v_fmac_f32_e32 v5, v4, v3
	v_add_f32_e32 v2, v5, v2
	v_and_b32_e32 v5, 64, v138
	v_xor_b32_e32 v3, 32, v138
	v_add_u32_e32 v5, 64, v5
	v_cmp_lt_i32_e32 vcc, v3, v5
	v_fmac_f32_e32 v12, v36, v36
	v_add_f32_e32 v11, v12, v11
	v_cndmask_b32_e32 v3, v138, v3, vcc
	v_lshlrev_b32_e32 v42, 2, v3
	ds_bpermute_b32 v3, v42, v2
	v_mul_f32_e32 v12, v40, v40
	v_fmac_f32_e32 v12, v35, v35
	v_add_f32_e32 v11, v12, v11
	v_mul_f32_e32 v12, v41, v41
	s_waitcnt lgkmcnt(0)
	v_add_f32_e32 v2, v2, v3
	v_xor_b32_e32 v3, 1, v138
	v_cmp_lt_i32_e32 vcc, v3, v5
	v_fmac_f32_e32 v12, v4, v4
	v_add_f32_e32 v4, v12, v11
	v_cndmask_b32_e32 v3, v138, v3, vcc
	v_lshlrev_b32_e32 v43, 2, v3
	ds_bpermute_b32 v3, v43, v2
	ds_bpermute_b32 v11, v42, v4
	s_waitcnt lgkmcnt(1)
	v_max_f32_e32 v3, v3, v3
	v_min_f32_e32 v2, v2, v3
	v_xor_b32_e32 v3, 2, v138
	v_cmp_lt_i32_e32 vcc, v3, v5
	s_waitcnt lgkmcnt(0)
	v_add_f32_e32 v4, v4, v11
	ds_bpermute_b32 v11, v43, v4
	v_cndmask_b32_e32 v3, v138, v3, vcc
	v_lshlrev_b32_e32 v44, 2, v3
	ds_bpermute_b32 v3, v44, v2
	s_waitcnt lgkmcnt(1)
	v_max_f32_e32 v11, v11, v11
	v_max_f32_e32 v4, v4, v11
	ds_bpermute_b32 v11, v44, v4
	s_waitcnt lgkmcnt(1)
	v_max_f32_e32 v3, v3, v3
	v_min_f32_e32 v2, v2, v3
	v_xor_b32_e32 v3, 4, v138
	v_cmp_lt_i32_e32 vcc, v3, v5
	s_waitcnt lgkmcnt(0)
	v_max_f32_e32 v11, v11, v11
	v_max_f32_e32 v4, v4, v11
	v_cndmask_b32_e32 v3, v138, v3, vcc
	v_lshlrev_b32_e32 v45, 2, v3
	ds_bpermute_b32 v3, v45, v2
	ds_bpermute_b32 v11, v45, v4
	s_waitcnt lgkmcnt(1)
	v_max_f32_e32 v3, v3, v3
	v_min_f32_e32 v2, v2, v3
	v_xor_b32_e32 v3, 8, v138
	v_cmp_lt_i32_e32 vcc, v3, v5
	s_waitcnt lgkmcnt(0)
	v_max_f32_e32 v11, v11, v11
	v_max_f32_e32 v4, v4, v11
	v_cndmask_b32_e32 v3, v138, v3, vcc
	v_lshlrev_b32_e32 v46, 2, v3
	ds_bpermute_b32 v3, v46, v2
	ds_bpermute_b32 v11, v46, v4
	s_waitcnt lgkmcnt(1)
	v_max_f32_e32 v3, v3, v3
	v_min_f32_e32 v2, v2, v3
	v_xor_b32_e32 v3, 16, v138
	v_cmp_lt_i32_e32 vcc, v3, v5
	s_waitcnt lgkmcnt(0)
	v_max_f32_e32 v11, v11, v11
	v_max_f32_e32 v4, v4, v11
	v_cndmask_b32_e32 v3, v138, v3, vcc
	v_lshlrev_b32_e32 v5, 2, v3
	ds_bpermute_b32 v3, v5, v2
	ds_bpermute_b32 v5, v5, v4
	v_cmp_eq_u32_e32 vcc, 0, v8
	s_and_saveexec_b64 s[0:1], vcc
	s_cbranch_execz .LBB0_505
	s_waitcnt lgkmcnt(1)
	v_max_f32_e32 v3, v3, v3
	v_max_f32_e32 v2, v2, v2
	v_readlane_b32 s3, v255, 2
	s_waitcnt lgkmcnt(0)
	v_max_f32_e32 v5, v5, v5
	v_max_f32_e32 v4, v4, v4
	v_min_f32_e32 v2, v2, v3
	v_mov_b32_e32 v3, s3
	v_max_f32_e32 v4, v4, v5
	v_add_u32_e32 v3, 0x9800, v3
	ds_write2_b32 v3, v2, v4 offset0:128 offset1:136
; __device__ __forceinline__ void attn_unit(const Args& a, LAS unsigned char* lds, const int mode, const int h, const int qb, const int tid_in, const int lane_in, const int wave) {
;     ...
;         __syncthreads();
;         float dmin = red[0], qn = red[8];
; #pragma unroll
;         for (int w = 1; w < 8; ++w) { dmin = fminf(dmin, red[w]); qn = fmaxf(qn, red[8 + w]); }
;         const float* N2 = (const float*)(ws + WS_N2); const float* PF = (const float*)(ws + WS_PFXP) + h * 256;
;         const float cq0 = (PF[qb * 4] + CLT[qb * 256]) * L2E, base = cq0 - dmin + 0.05f + 30.f;
;         int cnt = 0; bool open = true;
; #pragma unroll
;         for (int i = 0; i < 4; ++i) { const int j = lane + 64 * i; bool sk = false;
;             if (j < 4 * qb) sk = (base - PF[j + 1] * L2E + sqrtf(qn * N2[j * 32 + 16 + h]) * 1.01f) < 0.f;
;             const unsigned long long m = __ballot(sk); const bool full = (m == ~0ull);
;             if (open) cnt += full ? 64 : __builtin_ctzll(~m);
;             open = open && full; }
.LBB0_505:
	s_or_b64 exec, exec, s[0:1]
	s_waitcnt lgkmcnt(0)
	s_barrier
	ds_read_b128 v[2:5], v0 offset:39424
	ds_read_b128 v[12:15], v0 offset:39440
	ds_read_b128 v[16:19], v0 offset:39456
	ds_read_b128 v[20:23], v0 offset:39472
	s_lshl_b32 s0, s15, 2
	s_waitcnt lgkmcnt(3)
	v_max_f32_e32 v3, v3, v3
	v_max_f32_e32 v2, v2, v2
	v_min_f32_e32 v2, v2, v3
	s_waitcnt lgkmcnt(1)
	v_max_f32_e32 v3, v17, v17
	v_max_f32_e32 v11, v16, v16
	v_max_f32_e32 v3, v11, v3
	v_min3_f32 v2, v2, v4, v5
	v_max3_f32 v3, v3, v18, v19
	s_add_u32 s6, s60, s0
	v_min3_f32 v2, v2, v12, v13
	s_waitcnt lgkmcnt(0)
	v_max3_f32 v3, v3, v20, v21
	s_addc_u32 s7, s61, 0
	s_lshl_b32 s0, s16, 2
	v_min3_f32 v4, v2, v14, v15
	v_max3_f32 v2, v3, v22, v23
	v_mov_b32_e32 v3, s0
	s_lshl_b32 s0, s2, 2
	v_mov_b32_e32 v5, s0
	v_mov_b32_e32 v3, v240
	s_mov_b32 s0, 0x3fb8aa3b
	v_mov_b32_e32 v5, v241
	s_mov_b32 s1, 0x3f8147ae
	v_cmp_gt_u32_e32 vcc, s16, v8
	s_mov_b64 s[4:5], 0
	s_waitcnt vmcnt(0)
	v_add_f32_e32 v3, v3, v5
	v_fma_f32 v3, v3, s0, -v4
	v_add_f32_e32 v3, 0x3d4ccccd, v3
	v_add_f32_e32 v3, 0x41f00000, v3
	v_lshlrev_b32_e32 v4, 2, v8
	s_mov_b64 s[0:1], 0
	s_and_saveexec_b64 s[2:3], vcc
	s_cbranch_execz .LBB0_507
	s_lshl_b32 s0, s17, 2
	v_lshl_or_b32 v12, v8, 7, s0
	v_mov_b32_e32 v13, v0
	v_lshl_add_u64 v[12:13], s[88:89], 0, v[12:13]
	v_add_co_u32_e32 v12, vcc, 0x191000, v12
	s_nop 1
	v_addc_co_u32_e32 v13, vcc, 0, v13, vcc
	v_mov_b32_e32 v5, v246
	s_nop 0
	v_mov_b32_e32 v12, v242
	s_waitcnt vmcnt(1)
	v_mul_f32_e32 v5, v2, v5
	v_mul_f32_e32 v11, 0x4f800000, v5
	v_cmp_gt_f32_e32 vcc, s36, v5
	s_nop 1
	v_cndmask_b32_e32 v5, v5, v11, vcc
	v_sqrt_f32_e32 v11, v5
	s_nop 0
	v_add_u32_e32 v13, -1, v11
	v_add_u32_e32 v14, 1, v11
	v_fma_f32 v15, -v13, v11, v5
	v_fma_f32 v16, -v14, v11, v5
	v_cmp_ge_f32_e64 s[0:1], 0, v15
	s_nop 1
	v_cndmask_b32_e64 v11, v11, v13, s[0:1]
	v_cmp_lt_f32_e64 s[0:1], 0, v16
	s_nop 1
	v_cndmask_b32_e64 v11, v11, v14, s[0:1]
	v_mul_f32_e32 v13, 0x37800000, v11
	v_cndmask_b32_e32 v11, v11, v13, vcc
	v_cmp_class_f32_e32 vcc, v5, v131
	s_mov_b32 s0, 0x3fb8aa3b
	s_mov_b32 s1, 0x3f8147ae
	v_cndmask_b32_e32 v13, v11, v5, vcc
	s_waitcnt vmcnt(0)
	v_pk_mul_f32 v[12:13], v[12:13], s[0:1]
	s_nop 0
	v_sub_f32_e32 v5, v3, v12
	v_add_f32_e32 v5, v5, v13
	v_cmp_gt_f32_e32 vcc, 0, v5
	s_and_b64 s[0:1], vcc, exec
.LBB0_507:
	s_or_b64 exec, exec, s[2:3]
	v_cndmask_b32_e64 v5, 0, 1, s[0:1]
	v_cmp_ne_u32_e64 s[2:3], 0, v5
	v_or_b32_e32 v5, 64, v8
	v_cmp_gt_u32_e32 vcc, s16, v5
	s_and_saveexec_b64 s[10:11], vcc
	s_cbranch_execz .LBB0_509
	s_lshl_b32 s0, s17, 2
	v_lshl_or_b32 v12, v5, 7, s0
	v_mov_b32_e32 v13, v0
	v_lshl_add_u64 v[12:13], s[88:89], 0, v[12:13]
	v_add_co_u32_e32 v12, vcc, 0x191000, v12
	s_nop 1
	v_addc_co_u32_e32 v13, vcc, 0, v13, vcc
	v_mov_b32_e32 v5, v247
	s_nop 0
	v_mov_b32_e32 v12, v243
	s_waitcnt vmcnt(1)
	v_mul_f32_e32 v5, v2, v5
	v_mul_f32_e32 v11, 0x4f800000, v5
	v_cmp_gt_f32_e32 vcc, s36, v5
	s_nop 1
	v_cndmask_b32_e32 v5, v5, v11, vcc
	v_sqrt_f32_e32 v11, v5
	s_nop 0
	v_add_u32_e32 v13, -1, v11
	v_add_u32_e32 v14, 1, v11
	v_fma_f32 v15, -v13, v11, v5
	v_fma_f32 v16, -v14, v11, v5
	v_cmp_ge_f32_e64 s[0:1], 0, v15
	s_nop 1
	v_cndmask_b32_e64 v11, v11, v13, s[0:1]
	v_cmp_lt_f32_e64 s[0:1], 0, v16
	s_nop 1
	v_cndmask_b32_e64 v11, v11, v14, s[0:1]
	v_mul_f32_e32 v13, 0x37800000, v11
	v_cndmask_b32_e32 v11, v11, v13, vcc
	v_cmp_class_f32_e32 vcc, v5, v131
	s_mov_b32 s0, 0x3fb8aa3b
	s_mov_b32 s1, 0x3f8147ae
	v_cndmask_b32_e32 v13, v11, v5, vcc
	s_waitcnt vmcnt(0)
	v_pk_mul_f32 v[12:13], v[12:13], s[0:1]
	s_nop 0
	v_sub_f32_e32 v5, v3, v12
	v_add_f32_e32 v5, v5, v13
	v_cmp_gt_f32_e32 vcc, 0, v5
	s_and_b64 s[4:5], vcc, exec
.LBB0_509:
	s_or_b64 exec, exec, s[10:11]
	v_cndmask_b32_e64 v5, 0, 1, s[4:5]
	v_cmp_ne_u32_e64 s[0:1], 0, v5
	v_or_b32_e32 v5, 0x80, v8
	v_cmp_gt_u32_e32 vcc, s16, v5
	s_mov_b64 s[10:11], 0
	s_mov_b64 s[4:5], 0
	s_and_saveexec_b64 s[12:13], vcc
	s_cbranch_execz .LBB0_511
	s_lshl_b32 s4, s17, 2
	v_lshl_or_b32 v12, v5, 7, s4
	v_mov_b32_e32 v13, v0
	v_lshl_add_u64 v[12:13], s[88:89], 0, v[12:13]
	v_add_co_u32_e32 v12, vcc, 0x191000, v12
	s_nop 1
	v_addc_co_u32_e32 v13, vcc, 0, v13, vcc
	v_mov_b32_e32 v5, v248
	s_nop 0
	v_mov_b32_e32 v12, v244
	s_waitcnt vmcnt(1)
	v_mul_f32_e32 v5, v2, v5
	v_mul_f32_e32 v11, 0x4f800000, v5
	v_cmp_gt_f32_e32 vcc, s36, v5
	s_nop 1
	v_cndmask_b32_e32 v5, v5, v11, vcc
	v_sqrt_f32_e32 v11, v5
	s_nop 0
	v_add_u32_e32 v13, -1, v11
	v_add_u32_e32 v14, 1, v11
	v_fma_f32 v15, -v13, v11, v5
	v_fma_f32 v16, -v14, v11, v5
	v_cmp_ge_f32_e64 s[4:5], 0, v15
	s_nop 1
	v_cndmask_b32_e64 v11, v11, v13, s[4:5]
	v_cmp_lt_f32_e64 s[4:5], 0, v16
	s_nop 1
	v_cndmask_b32_e64 v11, v11, v14, s[4:5]
	v_mul_f32_e32 v13, 0x37800000, v11
	v_cndmask_b32_e32 v11, v11, v13, vcc
	v_cmp_class_f32_e32 vcc, v5, v131
	s_mov_b32 s4, 0x3fb8aa3b
	s_mov_b32 s5, 0x3f8147ae
	v_cndmask_b32_e32 v13, v11, v5, vcc
	s_waitcnt vmcnt(0)
	v_pk_mul_f32 v[12:13], v[12:13], s[4:5]
	s_nop 0
	v_sub_f32_e32 v5, v3, v12
	v_add_f32_e32 v5, v5, v13
	v_cmp_gt_f32_e32 vcc, 0, v5
	s_and_b64 s[4:5], vcc, exec
.LBB0_511:
	s_or_b64 exec, exec, s[12:13]
	v_cndmask_b32_e64 v5, 0, 1, s[4:5]
	v_cmp_ne_u32_e64 s[4:5], 0, v5
	v_or_b32_e32 v5, 0xc0, v8
	v_cmp_gt_u32_e32 vcc, s16, v5
	s_and_saveexec_b64 s[12:13], vcc
	s_cbranch_execz .LBB0_513
	v_mov_b32_e32 v4, v245
	s_lshl_b32 s6, s17, 2
	v_lshl_or_b32 v12, v5, 7, s6
	v_mov_b32_e32 v13, v0
	v_lshl_add_u64 v[12:13], s[88:89], 0, v[12:13]
	v_add_co_u32_e32 v12, vcc, 0x191000, v12
	s_nop 1
	v_addc_co_u32_e32 v13, vcc, 0, v13, vcc
	v_mov_b32_e32 v5, v249
	s_waitcnt vmcnt(0)
	v_mul_f32_e32 v2, v2, v5
	v_cmp_gt_f32_e32 vcc, s36, v2
	v_mul_f32_e32 v5, 0x4f800000, v2
	s_nop 0
	v_cndmask_b32_e32 v2, v2, v5, vcc
	v_sqrt_f32_e32 v5, v2
	s_nop 0
	v_add_u32_e32 v11, -1, v5
	v_fma_f32 v12, -v11, v5, v2
	v_cmp_ge_f32_e64 s[6:7], 0, v12
	v_add_u32_e32 v12, 1, v5
	s_nop 0
	v_cndmask_b32_e64 v11, v5, v11, s[6:7]
	v_fma_f32 v5, -v12, v5, v2
	v_cmp_lt_f32_e64 s[6:7], 0, v5
	s_nop 1
	v_cndmask_b32_e64 v5, v11, v12, s[6:7]
	v_mul_f32_e32 v11, 0x37800000, v5
	v_cndmask_b32_e32 v5, v5, v11, vcc
	v_cmp_class_f32_e32 vcc, v2, v131
	s_mov_b32 s6, 0x3fb8aa3b
	s_mov_b32 s7, 0x3f8147ae
	v_cndmask_b32_e32 v5, v5, v2, vcc
	v_pk_mul_f32 v[4:5], v[4:5], s[6:7]
	s_nop 0
	v_sub_f32_e32 v2, v3, v4
	v_add_f32_e32 v2, v2, v5
	v_cmp_gt_f32_e32 vcc, 0, v2
	s_and_b64 s[10:11], vcc, exec
